# loop-edge edit: the wave-uniform active-wave mask negation at the five attention main-loop heads done with s_not_b64 instead of v_cndmask + v_cmp through the VALU
# speedup vs baseline: 1.0107x; 1.0103x over previous
.LBB0_1482:
	s_not_b64 s[4:5], s[30:31]
	s_andn2_b64 vcc, exec, s[30:31]
	s_cbranch_vccnz .LBB0_1484
	ds_read_b128 v[100:103], v224
	ds_read_b128 v[104:107], v224 offset:32
	ds_read_b128 v[108:111], v224 offset:64
	s_waitcnt vmcnt(1)
	ds_read_b128 v[112:115], v224 offset:96
	ds_read_b128 v[84:87], v224 offset:128
	ds_read_b128 v[88:91], v224 offset:160
	ds_read_b128 v[92:95], v224 offset:192
	ds_read_b128 v[96:99], v224 offset:224
	ds_read_b128 v[2:5], v226 offset:49152
	ds_read_b128 v[6:9], v226 offset:57344
	ds_read_b128 v[10:13], v227 offset:49152
	ds_read_b128 v[80:83], v227 offset:57344
	ds_read_b128 v[116:119], v228 offset:49152
	ds_read_b128 v[120:123], v228 offset:57344
	s_waitcnt lgkmcnt(5)
	v_mfma_f32_32x32x16_bf16 v[100:115], v[2:5], v[172:175], v[100:115]
	ds_read_b128 v[2:5], v229 offset:49152
	s_waitcnt lgkmcnt(5)
	v_mfma_f32_32x32x16_bf16 v[84:99], v[6:9], v[172:175], v[84:99]
	ds_read_b128 v[6:9], v229 offset:57344
	s_waitcnt lgkmcnt(5)
	v_mfma_f32_32x32x16_bf16 v[100:115], v[10:13], v[168:171], v[100:115]
	ds_read_b128 v[10:13], v226 offset:49280
	s_waitcnt lgkmcnt(5)
	v_mfma_f32_32x32x16_bf16 v[84:99], v[80:83], v[168:171], v[84:99]
	ds_read_b128 v[80:83], v226 offset:57472
	s_waitcnt lgkmcnt(5)
	v_mfma_f32_32x32x16_bf16 v[100:115], v[116:119], v[164:167], v[100:115]
	ds_read_b128 v[116:119], v227 offset:49280
	s_waitcnt lgkmcnt(5)
	v_mfma_f32_32x32x16_bf16 v[84:99], v[120:123], v[164:167], v[84:99]
	ds_read_b128 v[120:123], v227 offset:57472
	s_waitcnt lgkmcnt(5)
	v_mfma_f32_32x32x16_bf16 v[100:115], v[2:5], v[160:163], v[100:115]
	ds_read_b128 v[2:5], v228 offset:49280
	s_waitcnt lgkmcnt(5)
	v_mfma_f32_32x32x16_bf16 v[84:99], v[6:9], v[160:163], v[84:99]
	ds_read_b128 v[6:9], v228 offset:57472
	s_waitcnt lgkmcnt(5)
	v_mfma_f32_32x32x16_bf16 v[100:115], v[10:13], v[156:159], v[100:115]
	ds_read_b128 v[10:13], v229 offset:49280
	s_waitcnt lgkmcnt(5)
	v_mfma_f32_32x32x16_bf16 v[84:99], v[80:83], v[156:159], v[84:99]
	ds_read_b128 v[80:83], v229 offset:57472
	s_waitcnt lgkmcnt(5)
	v_mfma_f32_32x32x16_bf16 v[100:115], v[116:119], v[152:155], v[100:115]
	s_waitcnt lgkmcnt(4)
	v_mfma_f32_32x32x16_bf16 v[84:99], v[120:123], v[152:155], v[84:99]
	s_waitcnt lgkmcnt(3)
	v_mfma_f32_32x32x16_bf16 v[100:115], v[2:5], v[148:151], v[100:115]
	s_waitcnt lgkmcnt(2)
	v_mfma_f32_32x32x16_bf16 v[84:99], v[6:9], v[148:151], v[84:99]
	s_waitcnt lgkmcnt(1)
	v_mfma_f32_32x32x16_bf16 v[100:115], v[10:13], v[144:147], v[100:115]
	s_waitcnt lgkmcnt(0)
	v_mfma_f32_32x32x16_bf16 v[84:99], v[80:83], v[144:147], v[84:99]
	s_branch .LBB0_1485

.LBB0_2854:
	s_not_b64 s[38:39], s[20:21]
	s_andn2_b64 vcc, exec, s[20:21]
	s_cbranch_vccnz .LBB0_2856
	ds_read_b128 v[100:103], v224
	ds_read_b128 v[104:107], v224 offset:32
	ds_read_b128 v[108:111], v224 offset:64
	s_waitcnt vmcnt(3)
	ds_read_b128 v[112:115], v224 offset:96
	ds_read_b128 v[84:87], v224 offset:128
	ds_read_b128 v[88:91], v224 offset:160
	ds_read_b128 v[92:95], v224 offset:192
	ds_read_b128 v[96:99], v224 offset:224
	ds_read_b128 v[2:5], v226 offset:49152
	ds_read_b128 v[6:9], v226 offset:57344
	ds_read_b128 v[10:13], v227 offset:49152
	ds_read_b128 v[80:83], v227 offset:57344
	ds_read_b128 v[116:119], v228 offset:49152
	ds_read_b128 v[120:123], v228 offset:57344
	s_waitcnt lgkmcnt(5)
	v_mfma_f32_32x32x16_bf16 v[100:115], v[2:5], v[172:175], v[100:115]
	ds_read_b128 v[2:5], v229 offset:49152
	s_waitcnt lgkmcnt(5)
	v_mfma_f32_32x32x16_bf16 v[84:99], v[6:9], v[172:175], v[84:99]
	ds_read_b128 v[6:9], v229 offset:57344
	s_waitcnt lgkmcnt(5)
	v_mfma_f32_32x32x16_bf16 v[100:115], v[10:13], v[168:171], v[100:115]
	ds_read_b128 v[10:13], v226 offset:49280
	s_waitcnt lgkmcnt(5)
	v_mfma_f32_32x32x16_bf16 v[84:99], v[80:83], v[168:171], v[84:99]
	ds_read_b128 v[80:83], v226 offset:57472
	s_waitcnt lgkmcnt(5)
	v_mfma_f32_32x32x16_bf16 v[100:115], v[116:119], v[164:167], v[100:115]
	ds_read_b128 v[116:119], v227 offset:49280
	s_waitcnt lgkmcnt(5)
	v_mfma_f32_32x32x16_bf16 v[84:99], v[120:123], v[164:167], v[84:99]
	ds_read_b128 v[120:123], v227 offset:57472
	s_waitcnt lgkmcnt(5)
	v_mfma_f32_32x32x16_bf16 v[100:115], v[2:5], v[160:163], v[100:115]
	ds_read_b128 v[2:5], v228 offset:49280
	s_waitcnt lgkmcnt(5)
	v_mfma_f32_32x32x16_bf16 v[84:99], v[6:9], v[160:163], v[84:99]
	ds_read_b128 v[6:9], v228 offset:57472
	s_waitcnt lgkmcnt(5)
	v_mfma_f32_32x32x16_bf16 v[100:115], v[10:13], v[156:159], v[100:115]
	ds_read_b128 v[10:13], v229 offset:49280
	s_waitcnt lgkmcnt(5)
	v_mfma_f32_32x32x16_bf16 v[84:99], v[80:83], v[156:159], v[84:99]
	ds_read_b128 v[80:83], v229 offset:57472
	s_waitcnt vmcnt(2) lgkmcnt(5)
	v_mfma_f32_32x32x16_bf16 v[100:115], v[116:119], v[152:155], v[100:115]
	s_waitcnt lgkmcnt(4)
	v_mfma_f32_32x32x16_bf16 v[84:99], v[120:123], v[152:155], v[84:99]
	s_waitcnt vmcnt(1) lgkmcnt(3)
	v_mfma_f32_32x32x16_bf16 v[100:115], v[2:5], v[148:151], v[100:115]
	s_waitcnt lgkmcnt(2)
	v_mfma_f32_32x32x16_bf16 v[84:99], v[6:9], v[148:151], v[84:99]
	s_waitcnt vmcnt(0) lgkmcnt(1)
	v_mfma_f32_32x32x16_bf16 v[100:115], v[10:13], v[144:147], v[100:115]
	s_waitcnt lgkmcnt(0)
	v_mfma_f32_32x32x16_bf16 v[84:99], v[80:83], v[144:147], v[84:99]
	s_branch .LBB0_2857
